# ffn2-up conversion beside rwkv_apply done by 2 waves per workgroup instead of 8 (fewer requests queued in the memory system)
# baseline (speedup 1.0000x reference)
.LBB0_990:
	s_and_b64 vcc, exec, s[4:5]
	s_cbranch_vccz .LBB0_1045
	s_mov_b64 s[0:1], -1
	s_and_b64 vcc, exec, s[12:13]
	s_cbranch_vccz .LBB0_1020
	s_sub_i32 s3, s2, 32
	s_lshl_b32 s0, s3, 1
	s_add_i32 s8, s57, s0
	s_cmp_ge_u32 s57, 2
	s_cselect_b32 s8, -1, s8
	s_waitcnt vmcnt(0)
	v_readlane_b32 s60, v240, 1
	v_readlane_b32 s61, v240, 2
	v_readlane_b32 s62, v240, 3
	v_readlane_b32 s63, v240, 4
	v_readlane_b32 s64, v240, 5
	v_readlane_b32 s65, v240, 6
	v_readlane_b32 s66, v240, 7
	v_readlane_b32 s67, v240, 8
	s_add_i32 s9, s80, 0xffffff00
	s_lshr_b32 s9, s9, 2
	s_mul_i32 s4, s57, 0x2100
	v_lshrrev_b32_e32 v55, 3, v146
	v_and_b32_e32 v56, 7, v146
	v_mul_u32_u24_e32 v44, 0x84, v55
	v_lshl_add_u32 v44, v56, 4, v44
	v_add_u32_e32 v44, s4, v44
	v_add_u32_e32 v45, 0x420, v44
	v_add_u32_e32 v46, 0x840, v44
	v_add_u32_e32 v47, 0xc60, v44
	v_add_u32_e32 v48, 0x1080, v44
	v_add_u32_e32 v49, 0x14a0, v44
	v_add_u32_e32 v50, 0x18c0, v44
	v_add_u32_e32 v51, 0x1ce0, v44
	v_mul_u32_u24_e32 v52, 0x420, v56
	v_lshl_add_u32 v52, v55, 2, v52
	v_add_u32_e32 v52, s4, v52
	v_lshrrev_b32_e32 v55, 3, v146
	v_and_b32_e32 v56, 7, v146
	s_mov_b32 s4, 0x5800
	v_mul_lo_u32 v53, v55, s4
	v_lshl_add_u32 v53, v56, 4, v53
	s_mov_b32 s4, 0x1000
	v_mul_lo_u32 v54, v55, s4
	v_lshl_add_u32 v54, v56, 4, v54
	s_mov_b32 s0, s8
	s_cmp_ge_u32 s0, 0x2c00
	s_cbranch_scc1 .Lcv_done_p7up
	s_lshr_b32 s10, s0, 5
	s_mul_i32 s10, s10, 0x1746
	s_lshr_b32 s10, s10, 16
	s_mul_i32 s11, s10, 352
	s_sub_u32 s11, s0, s11
	s_lshl_b32 s5, s11, 5
	s_lshr_b32 s6, s5, 8
	s_lshl_b32 s6, s6, 7
	s_and_b32 s7, s5, 0x7f
	s_add_u32 s6, s6, s7
	s_bitcmp1_b32 s5, 7
	s_mov_b32 s5, s6
	s_cselect_b32 s12, s64, s62
	s_cselect_b32 s13, s65, s63
	s_mul_i32 s6, s10, 0x160000
	s_lshl_b32 s5, s5, 2
	s_add_u32 s6, s6, s5
	s_add_u32 s12, s12, s6
	s_addc_u32 s13, s13, 0
	global_load_dwordx4 v[64:67], v53, s[12:13] nt
	s_add_u32 s12, s12, 0x2c000
	s_addc_u32 s13, s13, 0
	global_load_dwordx4 v[68:71], v53, s[12:13] nt
	s_add_u32 s12, s12, 0x2c000
	s_addc_u32 s13, s13, 0
	global_load_dwordx4 v[72:75], v53, s[12:13] nt
	s_add_u32 s12, s12, 0x2c000
	s_addc_u32 s13, s13, 0
	global_load_dwordx4 v[76:79], v53, s[12:13] nt
	s_add_u32 s12, s12, 0x2c000
	s_addc_u32 s13, s13, 0
	global_load_dwordx4 v[80:83], v53, s[12:13] nt
	s_add_u32 s12, s12, 0x2c000
	s_addc_u32 s13, s13, 0
	global_load_dwordx4 v[84:87], v53, s[12:13] nt
	s_add_u32 s12, s12, 0x2c000
	s_addc_u32 s13, s13, 0
	global_load_dwordx4 v[88:91], v53, s[12:13] nt
	s_add_u32 s12, s12, 0x2c000
	s_addc_u32 s13, s13, 0
	global_load_dwordx4 v[92:95], v53, s[12:13] nt
	s_add_u32 s1, s0, s9
	s_cmp_ge_u32 s1, 0x2c00
	s_cbranch_scc1 .Lcv_only1_p7up
	s_lshr_b32 s10, s1, 5
	s_mul_i32 s10, s10, 0x1746
	s_lshr_b32 s10, s10, 16
	s_mul_i32 s11, s10, 352
	s_sub_u32 s11, s1, s11
	s_lshl_b32 s5, s11, 5
	s_lshr_b32 s6, s5, 8
	s_lshl_b32 s6, s6, 7
	s_and_b32 s7, s5, 0x7f
	s_add_u32 s6, s6, s7
	s_bitcmp1_b32 s5, 7
	s_mov_b32 s5, s6
	s_cselect_b32 s12, s64, s62
	s_cselect_b32 s13, s65, s63
	s_mul_i32 s6, s10, 0x160000
	s_lshl_b32 s5, s5, 2
	s_add_u32 s6, s6, s5
	s_add_u32 s12, s12, s6
	s_addc_u32 s13, s13, 0
	global_load_dwordx4 v[96:99], v53, s[12:13] nt
	s_add_u32 s12, s12, 0x2c000
	s_addc_u32 s13, s13, 0
	global_load_dwordx4 v[100:103], v53, s[12:13] nt
	s_add_u32 s12, s12, 0x2c000
	s_addc_u32 s13, s13, 0
	global_load_dwordx4 v[104:107], v53, s[12:13] nt
	s_add_u32 s12, s12, 0x2c000
	s_addc_u32 s13, s13, 0
	global_load_dwordx4 v[108:111], v53, s[12:13] nt
	s_add_u32 s12, s12, 0x2c000
	s_addc_u32 s13, s13, 0
	global_load_dwordx4 v[112:115], v53, s[12:13] nt
	s_add_u32 s12, s12, 0x2c000
	s_addc_u32 s13, s13, 0
	global_load_dwordx4 v[116:119], v53, s[12:13] nt
	s_add_u32 s12, s12, 0x2c000
	s_addc_u32 s13, s13, 0
	global_load_dwordx4 v[120:123], v53, s[12:13] nt
	s_add_u32 s12, s12, 0x2c000
	s_addc_u32 s13, s13, 0
	global_load_dwordx4 v[124:127], v53, s[12:13] nt
	s_waitcnt vmcnt(8)
	s_branch .Lcv_procA_p7up
